# dynamic per-XCD unit queue for the 4th+ units of the two gate/up GEMM phases (atomic ticket two units ahead)
# baseline (speedup 1.0000x reference)
.LBB0_731:
	s_add_i32 s50, s50, 1
	s_mul_i32 s1, s75, s50
	s_mul_hi_u32 s2, s74, s50
	s_add_i32 s2, s2, s1
	s_mul_i32 s1, s74, s50
	s_add_u32 s24, s1, s93
	s_addc_u32 s25, s2, s73
	s_cmp_lg_u32 s74, 0x100
	s_cbranch_scc1 .Ldq6_done
	s_cmp_lg_u32 s75, 0
	s_cbranch_scc1 .Ldq6_done
	s_cmp_lt_u32 s50, 3
	s_cbranch_scc1 .Ldq6_lead
	s_and_b32 s94, s50, 1
	s_lshl_b32 s94, s94, 2
	s_add_i32 s94, s94, 0x25010
	v_mov_b32_e32 v231, s94
	ds_read_b32 v231, v231
	s_waitcnt lgkmcnt(0)
	v_readfirstlane_b32 s24, v231
	s_mov_b32 s25, 0
.Ldq6_lead:
	s_and_b64 vcc, exec, s[76:77]
	s_cbranch_vccnz .Ldq6_done
	s_load_dwordx2 s[60:61], s[82:83], 0xb0
	s_cmp_lt_u32 s50, 2
	s_cbranch_scc1 .Ldq6_ask
	v_readfirstlane_b32 s95, v230
	s_add_i32 s95, s95, 96
	s_lshl_b32 s95, s95, 3
	s_and_b32 s96, s93, 7
	s_or_b32 s95, s95, s96
	s_add_i32 s96, s50, 1
	s_and_b32 s96, s96, 1
	s_lshl_b32 s96, s96, 2
	s_add_i32 s96, s96, 0x25010
	v_mov_b32_e32 v231, s96
	v_mov_b32_e32 v232, s95
	ds_write_b32 v231, v232
.Ldq6_ask:
	s_and_b32 s96, s93, 7
	s_lshl_b32 s96, s96, 7
	s_add_i32 s96, s96, 0x3800
	v_mov_b32_e32 v231, s96
	v_mov_b32_e32 v232, 1
	s_mov_b64 s[98:99], exec
	s_waitcnt lgkmcnt(0)
	s_mov_b64 exec, 1
	s_nop 1
	global_atomic_add v230, v231, v232, s[60:61] sc0
	s_mov_b64 exec, s[98:99]
.Ldq6_done:
	v_cmp_gt_i64_e32 vcc, s[24:25], v[150:151]
	v_cmp_lt_i64_e64 s[6:7], s[24:25], v[148:149]
	s_cbranch_vccnz .LBB0_733
	s_ashr_i32 s1, s24, 31
	s_lshr_b32 s1, s1, 29
	s_add_i32 s1, s24, s1
	s_ashr_i32 s2, s1, 3
	s_and_b32 s1, s1, -8
	s_sub_i32 s1, s24, s1
	s_cmp_lt_i32 s1, 0
	s_cselect_b32 s5, s41, 0xbb
	s_mul_i32 s1, s1, s5
	s_add_i32 s1, s1, s2
	s_mul_hi_i32 s2, s1, 0x2e8ba2e9
	s_lshr_b32 s5, s2, 31
	s_ashr_i32 s2, s2, 4
	s_add_i32 s2, s2, s5
	s_lshl_b32 s5, s2, 2
	s_sub_i32 s20, 0x44, s5
	s_min_i32 s21, s20, 4
	s_abs_i32 s20, s21
	v_cvt_f32_u32_e32 v0, s20
	s_sub_i32 s23, 0, s20
	s_mulk_i32 s2, 0x58
	s_sub_i32 s1, s1, s2
	v_rcp_iflag_f32_e32 v0, v0
	s_abs_i32 s2, s1
	s_xor_b32 s22, s1, s21
	s_ashr_i32 s22, s22, 31
	v_mul_f32_e32 v0, 0x4f7ffffe, v0
	v_cvt_u32_f32_e32 v0, v0
	s_nop 0
	v_readfirstlane_b32 s24, v0
	s_mul_i32 s23, s23, s24
	s_mul_hi_u32 s23, s24, s23
	s_add_i32 s24, s24, s23
	s_mul_hi_u32 s23, s2, s24
	s_mul_i32 s24, s23, s20
	s_sub_i32 s2, s2, s24
	s_add_i32 s25, s23, 1
	s_sub_i32 s24, s2, s20
	s_cmp_ge_u32 s2, s20
	s_cselect_b32 s23, s25, s23
	s_cselect_b32 s2, s24, s2
	s_add_i32 s24, s23, 1
	s_cmp_ge_u32 s2, s20
	s_cselect_b32 s2, s24, s23
	s_xor_b32 s2, s2, s22
	s_sub_i32 s20, s2, s22
	s_mul_i32 s2, s20, s21
	s_sub_i32 s1, s1, s2
	s_add_i32 s22, s5, s1

.LBB0_1266:
	s_add_i32 s48, s48, 1
	s_mul_i32 s1, s75, s48
	s_mul_hi_u32 s2, s74, s48
	s_add_i32 s2, s2, s1
	s_mul_i32 s1, s74, s48
	s_add_u32 s24, s1, s93
	s_addc_u32 s25, s2, s73
	s_cmp_lg_u32 s74, 0x100
	s_cbranch_scc1 .Ldq12_done
	s_cmp_lg_u32 s75, 0
	s_cbranch_scc1 .Ldq12_done
	s_cmp_lt_u32 s48, 3
	s_cbranch_scc1 .Ldq12_lead
	s_and_b32 s94, s48, 1
	s_lshl_b32 s94, s94, 2
	s_add_i32 s94, s94, 0x25010
	v_mov_b32_e32 v231, s94
	ds_read_b32 v231, v231
	s_waitcnt lgkmcnt(0)
	v_readfirstlane_b32 s24, v231
	s_mov_b32 s25, 0
.Ldq12_lead:
	s_and_b64 vcc, exec, s[76:77]
	s_cbranch_vccnz .Ldq12_done
	s_load_dwordx2 s[60:61], s[82:83], 0xb0
	s_cmp_lt_u32 s48, 2
	s_cbranch_scc1 .Ldq12_ask
	v_readfirstlane_b32 s95, v230
	s_add_i32 s95, s95, 96
	s_lshl_b32 s95, s95, 3
	s_and_b32 s96, s93, 7
	s_or_b32 s95, s95, s96
	s_add_i32 s96, s48, 1
	s_and_b32 s96, s96, 1
	s_lshl_b32 s96, s96, 2
	s_add_i32 s96, s96, 0x25010
	v_mov_b32_e32 v231, s96
	v_mov_b32_e32 v232, s95
	ds_write_b32 v231, v232
.Ldq12_ask:
	s_and_b32 s96, s93, 7
	s_lshl_b32 s96, s96, 7
	s_add_i32 s96, s96, 0x3c00
	v_mov_b32_e32 v231, s96
	v_mov_b32_e32 v232, 1
	s_mov_b64 s[98:99], exec
	s_waitcnt lgkmcnt(0)
	s_mov_b64 exec, 1
	s_nop 1
	global_atomic_add v230, v231, v232, s[60:61] sc0
	s_mov_b64 exec, s[98:99]
.Ldq12_done:
	v_cmp_gt_i64_e32 vcc, s[24:25], v[150:151]
	v_cmp_lt_i64_e64 s[6:7], s[24:25], v[148:149]
	s_cbranch_vccnz .LBB0_1268
	s_ashr_i32 s1, s24, 31
	s_lshr_b32 s1, s1, 29
	s_add_i32 s1, s24, s1
	s_ashr_i32 s2, s1, 3
	s_and_b32 s1, s1, -8
	s_sub_i32 s1, s24, s1
	s_cmp_lt_i32 s1, 0
	s_cselect_b32 s5, s39, 0xb0
	s_mul_i32 s1, s1, s5
	s_add_i32 s1, s1, s2
	s_mul_hi_i32 s2, s1, 0x2e8ba2e9
	s_lshr_b32 s5, s2, 31
	s_ashr_i32 s2, s2, 4
	s_add_i32 s2, s2, s5
	s_lshl_b32 s5, s2, 2
	s_sub_i32 s20, 64, s5
	s_min_i32 s21, s20, 4
	s_abs_i32 s20, s21
	v_cvt_f32_u32_e32 v0, s20
	s_sub_i32 s23, 0, s20
	s_mulk_i32 s2, 0x58
	s_sub_i32 s1, s1, s2
	v_rcp_iflag_f32_e32 v0, v0
	s_abs_i32 s2, s1
	s_xor_b32 s22, s1, s21
	s_ashr_i32 s22, s22, 31
	v_mul_f32_e32 v0, 0x4f7ffffe, v0
	v_cvt_u32_f32_e32 v0, v0
	s_nop 0
	v_readfirstlane_b32 s24, v0
	s_mul_i32 s23, s23, s24
	s_mul_hi_u32 s23, s24, s23
	s_add_i32 s24, s24, s23
	s_mul_hi_u32 s23, s2, s24
	s_mul_i32 s24, s23, s20
	s_sub_i32 s2, s2, s24
	s_add_i32 s25, s23, 1
	s_sub_i32 s24, s2, s20
	s_cmp_ge_u32 s2, s20
	s_cselect_b32 s23, s25, s23
	s_cselect_b32 s2, s24, s2
	s_add_i32 s24, s23, 1
	s_cmp_ge_u32 s2, s20
	s_cselect_b32 s2, s24, s23
	s_xor_b32 s2, s2, s22
	s_sub_i32 s20, s2, s22
	s_mul_i32 s2, s20, s21
	s_sub_i32 s1, s1, s2
	s_add_i32 s22, s5, s1
